# combo13 + gate/up and w_in tile boundary: the older wave half runs its epilogue before (not after) its alignment barrier, overlapping the younger half's last MFMA segment
# speedup vs baseline: 1.0023x; 1.0023x over previous
; __device__ __forceinline__ unsigned cvt_pk_bf16(float lo, float hi) { unsigned r; asm volatile("v_cvt_pk_bf16_f32 %0, %1, %2" : "=v"(r) : "v"(lo), "v"(hi)); return r; }
; #define PG8_BAR __builtin_amdgcn_s_barrier()
; template <class Epi>
; __device__ __forceinline__ void gemm_phase(LAS unsigned char* lds, const Gemm g, const StaticOrder& S, const Epi& E, const int tid) {
;     ...
;         if (wr == 0) PG8_BAR;
;         E(acc, cur, wr, wc, fr, fq);
;     __device__ __forceinline__ void operator()(f32x4 (&acc)[2][2][4][2], const Unit& u, int wr, int wc, int fr, int fq) const {
;         const int row0 = u.pm * BM + wr * 64 + fr, col0 = u.pn * 128 + wc * 32 + 8 * fq;
; #pragma unroll
;         for (int ai = 0; ai < 2; ++ai)
; #pragma unroll
;             for (int m = 0; m < 4; ++m) {
;                 bf16* rowp = O + (size_t)(row0 + ai * HALF + m * 16) * FF + col0;
;                 const f32x4 g0 = acc[ai][0][m][0], g1 = acc[ai][0][m][1], u0 = acc[ai][1][m][0], u1 = acc[ai][1][m][1];
;                 u32x4 w;
;                 const f32x4 a0 = swiglu4(g0, u0), a1 = swiglu4(g1, u1);
;                 w.x = cvt_pk_bf16(a0[0], a0[1]); w.y = cvt_pk_bf16(a0[2], a0[3]); w.z = cvt_pk_bf16(a1[0], a1[1]); w.w = cvt_pk_bf16(a1[2], a1[3]);
;                 __builtin_nontemporal_store(w, (u32x4*)rowp);
;             }
.LBB0_164:
	s_setprio 0
	v_pk_mul_f32 v[150:151], v[126:127], s[74:75] op_sel_hi:[1,0]
	v_pk_mul_f32 v[152:153], v[124:125], s[74:75] op_sel_hi:[1,0]
	v_pk_mul_f32 v[122:123], v[126:127], v[122:123]
	v_pk_mul_f32 v[120:121], v[124:125], v[120:121]
	v_pk_mul_f32 v[124:125], v[118:119], s[74:75] op_sel_hi:[1,0]
	v_pk_mul_f32 v[126:127], v[116:117], s[74:75] op_sel_hi:[1,0]
	v_exp_f32_e32 v124, v124
	v_exp_f32_e32 v126, v126
	v_exp_f32_e32 v125, v125
	v_exp_f32_e32 v127, v127
	v_exp_f32_e32 v152, v152
	v_exp_f32_e32 v150, v150
	v_exp_f32_e32 v151, v151
	v_exp_f32_e32 v153, v153
	v_pk_add_f32 v[124:125], v[124:125], 1.0 op_sel_hi:[1,0]
	v_pk_add_f32 v[126:127], v[126:127], 1.0 op_sel_hi:[1,0]
	v_pk_add_f32 v[150:151], v[150:151], 1.0 op_sel_hi:[1,0]
	v_pk_add_f32 v[152:153], v[152:153], 1.0 op_sel_hi:[1,0]
	v_rcp_f32_e32 v126, v126
	v_rcp_f32_e32 v124, v124
	v_rcp_f32_e32 v125, v125
	v_rcp_f32_e32 v127, v127
	v_readlane_b32 s0, v254, 23
	v_rcp_f32_e32 v152, v152
	v_rcp_f32_e32 v153, v153
	v_rcp_f32_e32 v150, v150
	v_rcp_f32_e32 v151, v151
	v_lshl_or_b32 v140, s49, 7, v144
	v_readlane_b32 s1, v254, 24
	v_lshl_add_u32 v146, s52, 8, v142
	v_ashrrev_i32_e32 v141, 31, v140
	v_mov_b64_e32 v[138:139], s[0:1]
	s_movk_i32 s2, 0x2c00
	v_pk_mul_f32 v[114:115], v[118:119], v[114:115]
	v_pk_mul_f32 v[112:113], v[116:117], v[112:113]
	v_mad_i64_i32 v[148:149], s[0:1], v146, s2, v[138:139]
	v_lshlrev_b64 v[140:141], 1, v[140:141]
	v_pk_mul_f32 v[116:117], v[124:125], v[114:115]
	v_pk_mul_f32 v[114:115], v[126:127], v[112:113]
	v_lshl_add_u64 v[148:149], v[148:149], 0, v[140:141]
	v_pk_mul_f32 v[122:123], v[150:151], v[122:123]
	v_pk_mul_f32 v[120:121], v[152:153], v[120:121]
	v_pk_mul_f32 v[106:107], v[110:111], v[106:107]
	v_cvt_pk_bf16_f32 v112, v120, v121
	v_cvt_pk_bf16_f32 v113, v122, v123
	v_cvt_pk_bf16_f32 v114, v114, v115
	v_cvt_pk_bf16_f32 v115, v116, v117
	global_store_dwordx4 v[148:149], v[112:115], off nt
	v_pk_mul_f32 v[104:105], v[108:109], v[104:105]
	v_or_b32_e32 v116, 16, v146
	v_pk_mul_f32 v[112:113], v[110:111], s[74:75] op_sel_hi:[1,0]
	v_pk_mul_f32 v[114:115], v[108:109], s[74:75] op_sel_hi:[1,0]
	v_pk_mul_f32 v[108:109], v[102:103], s[74:75] op_sel_hi:[1,0]
	v_pk_mul_f32 v[110:111], v[100:101], s[74:75] op_sel_hi:[1,0]
	v_exp_f32_e32 v108, v108
	v_exp_f32_e32 v110, v110
	v_exp_f32_e32 v109, v109
	v_exp_f32_e32 v111, v111
	v_exp_f32_e32 v114, v114
	v_exp_f32_e32 v115, v115
	v_exp_f32_e32 v112, v112
	v_exp_f32_e32 v113, v113
	v_pk_add_f32 v[108:109], v[108:109], 1.0 op_sel_hi:[1,0]
	v_pk_add_f32 v[110:111], v[110:111], 1.0 op_sel_hi:[1,0]
	v_pk_add_f32 v[114:115], v[114:115], 1.0 op_sel_hi:[1,0]
	v_pk_add_f32 v[112:113], v[112:113], 1.0 op_sel_hi:[1,0]
	v_rcp_f32_e32 v110, v110
	v_rcp_f32_e32 v108, v108
	v_rcp_f32_e32 v109, v109
	v_rcp_f32_e32 v111, v111
	v_rcp_f32_e32 v114, v114
	v_rcp_f32_e32 v115, v115
	v_rcp_f32_e32 v112, v112
	v_rcp_f32_e32 v113, v113
	v_pk_mul_f32 v[98:99], v[102:103], v[98:99]
	v_pk_mul_f32 v[96:97], v[100:101], v[96:97]
	v_mad_i64_i32 v[116:117], s[0:1], v116, s2, v[138:139]
	v_pk_mul_f32 v[100:101], v[108:109], v[98:99]
	v_pk_mul_f32 v[98:99], v[110:111], v[96:97]
	v_lshl_add_u64 v[116:117], v[116:117], 0, v[140:141]
	v_pk_mul_f32 v[106:107], v[112:113], v[106:107]
	v_pk_mul_f32 v[104:105], v[114:115], v[104:105]
	v_pk_mul_f32 v[90:91], v[94:95], v[90:91]
	v_cvt_pk_bf16_f32 v96, v104, v105
	v_cvt_pk_bf16_f32 v97, v106, v107
	v_cvt_pk_bf16_f32 v98, v98, v99
	v_cvt_pk_bf16_f32 v99, v100, v101
	global_store_dwordx4 v[116:117], v[96:99], off nt
	v_pk_mul_f32 v[88:89], v[92:93], v[88:89]
	v_or_b32_e32 v100, 32, v146
	v_pk_mul_f32 v[96:97], v[94:95], s[74:75] op_sel_hi:[1,0]
	v_pk_mul_f32 v[98:99], v[92:93], s[74:75] op_sel_hi:[1,0]
	v_pk_mul_f32 v[92:93], v[86:87], s[74:75] op_sel_hi:[1,0]
	v_pk_mul_f32 v[94:95], v[84:85], s[74:75] op_sel_hi:[1,0]
	v_exp_f32_e32 v92, v92
	v_exp_f32_e32 v94, v94
	v_exp_f32_e32 v93, v93
	v_exp_f32_e32 v95, v95
	v_exp_f32_e32 v98, v98
	v_exp_f32_e32 v99, v99
	v_exp_f32_e32 v96, v96
	v_exp_f32_e32 v97, v97
	v_pk_add_f32 v[92:93], v[92:93], 1.0 op_sel_hi:[1,0]
	v_pk_add_f32 v[94:95], v[94:95], 1.0 op_sel_hi:[1,0]
	v_pk_add_f32 v[98:99], v[98:99], 1.0 op_sel_hi:[1,0]
	v_pk_add_f32 v[96:97], v[96:97], 1.0 op_sel_hi:[1,0]
	v_rcp_f32_e32 v94, v94
	v_rcp_f32_e32 v92, v92
	v_rcp_f32_e32 v93, v93
	v_rcp_f32_e32 v95, v95
	v_rcp_f32_e32 v98, v98
	v_rcp_f32_e32 v99, v99
	v_rcp_f32_e32 v96, v96
	v_rcp_f32_e32 v97, v97
	v_pk_mul_f32 v[82:83], v[86:87], v[82:83]
	v_pk_mul_f32 v[80:81], v[84:85], v[80:81]
	v_mad_i64_i32 v[100:101], s[0:1], v100, s2, v[138:139]
	v_pk_mul_f32 v[84:85], v[92:93], v[82:83]
	v_pk_mul_f32 v[82:83], v[94:95], v[80:81]
	v_lshl_add_u64 v[100:101], v[100:101], 0, v[140:141]
	v_pk_mul_f32 v[90:91], v[96:97], v[90:91]
	v_pk_mul_f32 v[88:89], v[98:99], v[88:89]
	v_pk_mul_f32 v[74:75], v[78:79], v[74:75]
	v_cvt_pk_bf16_f32 v80, v88, v89
	v_cvt_pk_bf16_f32 v81, v90, v91
	v_cvt_pk_bf16_f32 v82, v82, v83
	v_cvt_pk_bf16_f32 v83, v84, v85
	global_store_dwordx4 v[100:101], v[80:83], off nt
	v_pk_mul_f32 v[72:73], v[76:77], v[72:73]
	v_or_b32_e32 v84, 48, v146
	v_pk_mul_f32 v[80:81], v[78:79], s[74:75] op_sel_hi:[1,0]
	v_pk_mul_f32 v[82:83], v[76:77], s[74:75] op_sel_hi:[1,0]
	v_pk_mul_f32 v[76:77], v[70:71], s[74:75] op_sel_hi:[1,0]
	v_pk_mul_f32 v[78:79], v[68:69], s[74:75] op_sel_hi:[1,0]
	v_exp_f32_e32 v76, v76
	v_exp_f32_e32 v78, v78
	v_exp_f32_e32 v77, v77
	v_exp_f32_e32 v79, v79
	v_exp_f32_e32 v82, v82
	v_exp_f32_e32 v83, v83
	v_exp_f32_e32 v80, v80
	v_exp_f32_e32 v81, v81
	v_pk_add_f32 v[76:77], v[76:77], 1.0 op_sel_hi:[1,0]
	v_pk_add_f32 v[78:79], v[78:79], 1.0 op_sel_hi:[1,0]
; __device__ __forceinline__ unsigned cvt_pk_bf16(float lo, float hi) { unsigned r; asm volatile("v_cvt_pk_bf16_f32 %0, %1, %2" : "=v"(r) : "v"(lo), "v"(hi)); return r; }
; #define PG8_BAR __builtin_amdgcn_s_barrier()
; template <class Epi>
; __device__ __forceinline__ void gemm_phase(LAS unsigned char* lds, const Gemm g, const StaticOrder& S, const Epi& E, const int tid) {
;     ...
;         if (wr == 0) PG8_BAR;
;         E(acc, cur, wr, wc, fr, fq);
;     __device__ __forceinline__ void operator()(f32x4 (&acc)[2][2][4][2], const Unit& u, int wr, int wc, int fr, int fq) const {
;     ...
;             for (int m = 0; m < 4; ++m) {
;                 bf16* rowp = O + (size_t)(row0 + ai * HALF + m * 16) * FF + col0;
;                 const f32x4 g0 = acc[ai][0][m][0], g1 = acc[ai][0][m][1], u0 = acc[ai][1][m][0], u1 = acc[ai][1][m][1];
;                 u32x4 w;
;                 const f32x4 a0 = swiglu4(g0, u0), a1 = swiglu4(g1, u1);
;                 w.x = cvt_pk_bf16(a0[0], a0[1]); w.y = cvt_pk_bf16(a0[2], a0[3]); w.z = cvt_pk_bf16(a1[0], a1[1]); w.w = cvt_pk_bf16(a1[2], a1[3]);
;                 __builtin_nontemporal_store(w, (u32x4*)rowp);
;             }
	v_pk_add_f32 v[82:83], v[82:83], 1.0 op_sel_hi:[1,0]
	v_pk_add_f32 v[80:81], v[80:81], 1.0 op_sel_hi:[1,0]
	v_rcp_f32_e32 v78, v78
	v_rcp_f32_e32 v76, v76
	v_rcp_f32_e32 v77, v77
	v_rcp_f32_e32 v79, v79
	v_rcp_f32_e32 v82, v82
	v_rcp_f32_e32 v83, v83
	v_rcp_f32_e32 v80, v80
	v_rcp_f32_e32 v81, v81
	v_pk_mul_f32 v[66:67], v[70:71], v[66:67]
	v_pk_mul_f32 v[64:65], v[68:69], v[64:65]
	v_mad_i64_i32 v[84:85], s[0:1], v84, s2, v[138:139]
	v_pk_mul_f32 v[68:69], v[76:77], v[66:67]
	v_pk_mul_f32 v[66:67], v[78:79], v[64:65]
	v_lshl_add_u64 v[84:85], v[84:85], 0, v[140:141]
	v_pk_mul_f32 v[74:75], v[80:81], v[74:75]
	v_pk_mul_f32 v[72:73], v[82:83], v[72:73]
	v_pk_mul_f32 v[58:59], v[62:63], v[58:59]
	v_cvt_pk_bf16_f32 v64, v72, v73
	v_cvt_pk_bf16_f32 v65, v74, v75
	v_cvt_pk_bf16_f32 v66, v66, v67
	v_cvt_pk_bf16_f32 v67, v68, v69
	global_store_dwordx4 v[84:85], v[64:67], off nt
	v_pk_mul_f32 v[56:57], v[60:61], v[56:57]
	v_add_u32_e32 v68, 0x80, v146
	v_pk_mul_f32 v[64:65], v[62:63], s[74:75] op_sel_hi:[1,0]
	v_pk_mul_f32 v[66:67], v[60:61], s[74:75] op_sel_hi:[1,0]
	v_pk_mul_f32 v[60:61], v[54:55], s[74:75] op_sel_hi:[1,0]
	v_pk_mul_f32 v[62:63], v[52:53], s[74:75] op_sel_hi:[1,0]
	v_exp_f32_e32 v60, v60
	v_exp_f32_e32 v62, v62
	v_exp_f32_e32 v61, v61
	v_exp_f32_e32 v63, v63
	v_exp_f32_e32 v66, v66
	v_exp_f32_e32 v67, v67
	v_exp_f32_e32 v64, v64
	v_exp_f32_e32 v65, v65
	v_pk_add_f32 v[60:61], v[60:61], 1.0 op_sel_hi:[1,0]
	v_pk_add_f32 v[62:63], v[62:63], 1.0 op_sel_hi:[1,0]
	v_pk_add_f32 v[66:67], v[66:67], 1.0 op_sel_hi:[1,0]
	v_pk_add_f32 v[64:65], v[64:65], 1.0 op_sel_hi:[1,0]
	v_rcp_f32_e32 v62, v62
	v_rcp_f32_e32 v60, v60
	v_rcp_f32_e32 v61, v61
	v_rcp_f32_e32 v63, v63
	v_rcp_f32_e32 v66, v66
	v_rcp_f32_e32 v67, v67
	v_rcp_f32_e32 v64, v64
	v_rcp_f32_e32 v65, v65
	v_pk_mul_f32 v[50:51], v[54:55], v[50:51]
	v_pk_mul_f32 v[48:49], v[52:53], v[48:49]
	v_mad_i64_i32 v[68:69], s[0:1], v68, s2, v[138:139]
	v_pk_mul_f32 v[52:53], v[60:61], v[50:51]
	v_pk_mul_f32 v[50:51], v[62:63], v[48:49]
	v_lshl_add_u64 v[68:69], v[68:69], 0, v[140:141]
	v_pk_mul_f32 v[58:59], v[64:65], v[58:59]
	v_pk_mul_f32 v[56:57], v[66:67], v[56:57]
	v_pk_mul_f32 v[42:43], v[46:47], v[42:43]
	v_cvt_pk_bf16_f32 v48, v56, v57
	v_cvt_pk_bf16_f32 v49, v58, v59
	v_cvt_pk_bf16_f32 v50, v50, v51
	v_cvt_pk_bf16_f32 v51, v52, v53
	global_store_dwordx4 v[68:69], v[48:51], off nt
	v_pk_mul_f32 v[40:41], v[44:45], v[40:41]
	v_add_u32_e32 v52, 0x90, v146
	v_pk_mul_f32 v[48:49], v[46:47], s[74:75] op_sel_hi:[1,0]
	v_pk_mul_f32 v[50:51], v[44:45], s[74:75] op_sel_hi:[1,0]
	v_pk_mul_f32 v[44:45], v[38:39], s[74:75] op_sel_hi:[1,0]
	v_pk_mul_f32 v[46:47], v[36:37], s[74:75] op_sel_hi:[1,0]
	v_exp_f32_e32 v44, v44
	v_exp_f32_e32 v46, v46
	v_exp_f32_e32 v45, v45
	v_exp_f32_e32 v47, v47
	v_exp_f32_e32 v50, v50
	v_exp_f32_e32 v51, v51
	v_exp_f32_e32 v48, v48
	v_exp_f32_e32 v49, v49
	v_pk_add_f32 v[44:45], v[44:45], 1.0 op_sel_hi:[1,0]
	v_pk_add_f32 v[46:47], v[46:47], 1.0 op_sel_hi:[1,0]
	v_pk_add_f32 v[50:51], v[50:51], 1.0 op_sel_hi:[1,0]
	v_pk_add_f32 v[48:49], v[48:49], 1.0 op_sel_hi:[1,0]
	v_rcp_f32_e32 v46, v46
	v_rcp_f32_e32 v44, v44
	v_rcp_f32_e32 v45, v45
	v_rcp_f32_e32 v47, v47
	v_rcp_f32_e32 v50, v50
	v_rcp_f32_e32 v51, v51
	v_rcp_f32_e32 v48, v48
	v_rcp_f32_e32 v49, v49
	v_pk_mul_f32 v[34:35], v[38:39], v[34:35]
	v_pk_mul_f32 v[32:33], v[36:37], v[32:33]
	v_mad_i64_i32 v[52:53], s[0:1], v52, s2, v[138:139]
	v_pk_mul_f32 v[36:37], v[44:45], v[34:35]
	v_pk_mul_f32 v[34:35], v[46:47], v[32:33]
	v_lshl_add_u64 v[52:53], v[52:53], 0, v[140:141]
	v_pk_mul_f32 v[42:43], v[48:49], v[42:43]
	v_pk_mul_f32 v[40:41], v[50:51], v[40:41]
	v_pk_mul_f32 v[26:27], v[30:31], v[26:27]
	v_cvt_pk_bf16_f32 v32, v40, v41
	v_cvt_pk_bf16_f32 v33, v42, v43
	v_cvt_pk_bf16_f32 v34, v34, v35
	v_cvt_pk_bf16_f32 v35, v36, v37
	global_store_dwordx4 v[52:53], v[32:35], off nt
	v_pk_mul_f32 v[24:25], v[28:29], v[24:25]
	v_add_u32_e32 v36, 0xa0, v146
	v_pk_mul_f32 v[32:33], v[30:31], s[74:75] op_sel_hi:[1,0]
	v_pk_mul_f32 v[34:35], v[28:29], s[74:75] op_sel_hi:[1,0]
	v_pk_mul_f32 v[28:29], v[22:23], s[74:75] op_sel_hi:[1,0]
	v_pk_mul_f32 v[30:31], v[20:21], s[74:75] op_sel_hi:[1,0]
	v_exp_f32_e32 v28, v28
	v_exp_f32_e32 v30, v30
	v_exp_f32_e32 v29, v29
	v_exp_f32_e32 v31, v31
	v_exp_f32_e32 v34, v34
	v_exp_f32_e32 v35, v35
	v_exp_f32_e32 v32, v32
	v_exp_f32_e32 v33, v33
	v_pk_add_f32 v[28:29], v[28:29], 1.0 op_sel_hi:[1,0]
	v_pk_add_f32 v[30:31], v[30:31], 1.0 op_sel_hi:[1,0]
	v_pk_add_f32 v[34:35], v[34:35], 1.0 op_sel_hi:[1,0]
	v_pk_add_f32 v[32:33], v[32:33], 1.0 op_sel_hi:[1,0]
	v_rcp_f32_e32 v30, v30
	v_rcp_f32_e32 v28, v28
	v_rcp_f32_e32 v29, v29
	v_rcp_f32_e32 v31, v31
	v_rcp_f32_e32 v34, v34
	v_rcp_f32_e32 v35, v35
	v_rcp_f32_e32 v32, v32
	v_rcp_f32_e32 v33, v33
	v_pk_mul_f32 v[18:19], v[22:23], v[18:19]
	v_pk_mul_f32 v[16:17], v[20:21], v[16:17]
	v_mad_i64_i32 v[36:37], s[0:1], v36, s2, v[138:139]
	v_pk_mul_f32 v[20:21], v[28:29], v[18:19]
	v_pk_mul_f32 v[18:19], v[30:31], v[16:17]
	v_lshl_add_u64 v[36:37], v[36:37], 0, v[140:141]
	v_pk_mul_f32 v[26:27], v[32:33], v[26:27]
	v_pk_mul_f32 v[24:25], v[34:35], v[24:25]
	v_pk_mul_f32 v[10:11], v[14:15], v[10:11]
	v_cvt_pk_bf16_f32 v16, v24, v25
	v_cvt_pk_bf16_f32 v17, v26, v27
	v_cvt_pk_bf16_f32 v18, v18, v19
	v_cvt_pk_bf16_f32 v19, v20, v21
	global_store_dwordx4 v[36:37], v[16:19], off nt
	v_pk_mul_f32 v[8:9], v[12:13], v[8:9]
	v_add_u32_e32 v20, 0xb0, v146
	v_pk_mul_f32 v[16:17], v[14:15], s[74:75] op_sel_hi:[1,0]
	v_pk_mul_f32 v[18:19], v[12:13], s[74:75] op_sel_hi:[1,0]
	v_pk_mul_f32 v[12:13], v[6:7], s[74:75] op_sel_hi:[1,0]
	v_pk_mul_f32 v[14:15], v[4:5], s[74:75] op_sel_hi:[1,0]
	v_exp_f32_e32 v12, v12
	v_exp_f32_e32 v14, v14
	v_exp_f32_e32 v13, v13
	v_exp_f32_e32 v15, v15
	v_exp_f32_e32 v18, v18
	v_exp_f32_e32 v19, v19
	v_exp_f32_e32 v16, v16
	v_exp_f32_e32 v17, v17
	v_pk_add_f32 v[12:13], v[12:13], 1.0 op_sel_hi:[1,0]
	v_pk_add_f32 v[14:15], v[14:15], 1.0 op_sel_hi:[1,0]
	v_pk_add_f32 v[18:19], v[18:19], 1.0 op_sel_hi:[1,0]
	v_pk_add_f32 v[16:17], v[16:17], 1.0 op_sel_hi:[1,0]
	v_rcp_f32_e32 v14, v14
	v_rcp_f32_e32 v12, v12
	v_rcp_f32_e32 v13, v13
	v_rcp_f32_e32 v15, v15
	v_rcp_f32_e32 v18, v18
	v_rcp_f32_e32 v19, v19
	v_rcp_f32_e32 v16, v16
	v_rcp_f32_e32 v17, v17
	v_mad_i64_i32 v[20:21], s[0:1], v20, s2, v[138:139]
	v_pk_mul_f32 v[2:3], v[6:7], v[2:3]
	v_pk_mul_f32 v[0:1], v[4:5], v[0:1]
	v_lshl_add_u64 v[20:21], v[20:21], 0, v[140:141]
	v_pk_mul_f32 v[4:5], v[12:13], v[2:3]
	v_pk_mul_f32 v[2:3], v[14:15], v[0:1]
	s_andn2_b64 vcc, exec, s[36:37]
	s_mov_b64 s[0:1], -1
	v_readlane_b32 s58, v254, 62
	v_readlane_b32 s59, v254, 63
	v_pk_mul_f32 v[10:11], v[16:17], v[10:11]
	v_pk_mul_f32 v[8:9], v[18:19], v[8:9]
	s_nop 0
	v_cvt_pk_bf16_f32 v0, v8, v9
	v_cvt_pk_bf16_f32 v1, v10, v11
	v_cvt_pk_bf16_f32 v2, v2, v3
	v_cvt_pk_bf16_f32 v3, v4, v5
	global_store_dwordx4 v[20:21], v[0:3], off nt
	s_cmp_eq_u64 s[10:11], 0
	s_cbranch_scc1 .Lepi_gu1_nb
	s_barrier

; #define PG8_STAGE(bufoff, gbase, voff) do { _Pragma("unroll") for (int _i = 0; _i < 2; ++_i) \
;         __builtin_amdgcn_global_load_lds((const unsigned*)((const char*)(gbase) + (voff)[_i]), (LAS unsigned*)(lds + (bufoff) + ldsw + _i * 8192), 16, 0, 0); } while (0)
; #define PG8_LDA(dst, b, h) do { _Pragma("unroll") for (int m = 0; m < 4; ++m) _Pragma("unroll") for (int k = 0; k < 2; ++k) dst[m][k] = *(const LAS bf16x8*)(lds + PG8_SA(b, h) + aoff + m * 2048 + k * 1024); } while (0)
; #define PG8_LDB(dst, b, h) do { _Pragma("unroll") for (int n = 0; n < 2; ++n) _Pragma("unroll") for (int k = 0; k < 2; ++k) dst[n][k] = *(const LAS bf16x8*)(lds + PG8_SB(b, h) + boff + n * 2048 + k * 1024); } while (0)
; #define PG8_MMA(ai, bj, At, Bt) do { __builtin_amdgcn_s_setprio(1); _Pragma("unroll") for (int m = 0; m < 4; ++m) _Pragma("unroll") for (int n = 0; n < 2; ++n) _Pragma("unroll") for (int k = 0; k < 2; ++k) \
;         acc[ai][bj][m][n] = __builtin_amdgcn_mfma_f32_16x16x32_bf16(Bt[n][k], At[m][k], acc[ai][bj][m][n], 0, 0, 0); __builtin_amdgcn_s_setprio(0); } while (0)
; #define PG8_WAIT_V(n) asm volatile("s_waitcnt vmcnt(" #n ")" ::: "memory")
; #define PG8_WAIT_L(n) asm volatile("s_waitcnt lgkmcnt(" #n ")" ::: "memory")
; #define PG8_BAR __builtin_amdgcn_s_barrier()
; #define PG8_SCHED __builtin_amdgcn_sched_barrier(0)
; template <class Epi>
; __device__ __forceinline__ void gemm_phase(LAS unsigned char* lds, const Gemm g, const StaticOrder& S, const Epi& E, const int tid) {
;     ...
;             PG8_LDB(B0, 0, 0); PG8_LDB(B1, 0, 1); PG8_SCHED; PG8_LDA(At, 0, 0); PG8_STAGE(PG8_SA(1, 1), a1 + hsA, voffA);
;             PG8_WAIT_V(8); PG8_WAIT_L(0); PG8_BAR; PG8_MMA(0, 0, At, B0); PG8_MMA(0, 1, At, B1); PG8_BAR; PG8_SCHED;
;             PG8_LDA(At, 0, 1); PG8_STAGE(PG8_SB(0, 0), b2, voffB); PG8_STAGE(PG8_SB(0, 1), b2 + hsB, voffB); PG8_STAGE(PG8_SA(0, 0), a2, voffA);
;             PG8_WAIT_V(8); PG8_WAIT_L(0); PG8_BAR; PG8_MMA(1, 0, At, B0); PG8_MMA(1, 1, At, B1); PG8_BAR; PG8_SCHED;
.Lgprio_c:
.LBB0_354:
	s_add_u32 s0, s36, 0xfff80080
	s_addc_u32 s1, s37, -1
	s_add_i32 s24, 0, 0x10000
	s_cmp_eq_u32 vcc_hi, 28
	s_cselect_b32 s43, s10, s1
	s_cselect_b32 s42, s11, s0
	v_add_u32_e32 v143, s24, v163
	s_cselect_b32 s1, s47, vcc_lo
	s_cselect_b32 s0, s49, s69
	s_add_i32 s55, 0, 0x14000
	ds_read_b128 v[144:147], v143
	ds_read_b128 v[148:151], v143 offset:1024
	ds_read_b128 v[152:155], v143 offset:2048
	ds_read_b128 v[156:159], v143 offset:3072
	v_add_u32_e32 v143, s55, v163
	ds_read_b128 v[184:187], v143
	ds_read_b128 v[188:191], v143 offset:1024
	ds_read_b128 v[192:195], v143 offset:2048
	ds_read_b128 v[196:199], v143 offset:3072
	v_lshl_add_u64 v[160:161], s[36:37], 0, v[138:139]
	s_add_i32 m0, s58, 0xc000
	ds_read_b128 v[200:203], v165
	ds_read_b128 v[204:207], v165 offset:1024
	ds_read_b128 v[208:211], v165 offset:2048
	ds_read_b128 v[232:235], v165 offset:3072
	ds_read_b128 v[236:239], v165 offset:4096
	ds_read_b128 v[240:243], v165 offset:5120
	ds_read_b128 v[244:247], v165 offset:6144
	ds_read_b128 v[248:251], v165 offset:7168
	global_load_lds_dwordx4 v[160:161], off
	v_lshl_add_u64 v[160:161], s[36:37], 0, v[140:141]
	s_add_i32 m0, s58, 0xe000
	s_nop 0
	global_load_lds_dwordx4 v[160:161], off
	s_waitcnt vmcnt(8)
	s_waitcnt lgkmcnt(0)
	s_barrier
	v_mfma_f32_16x16x32_bf16 v[124:127], v[144:147], v[200:203], v[124:127]
	v_mfma_f32_16x16x32_bf16 v[120:123], v[152:155], v[200:203], v[120:123]
	v_mfma_f32_16x16x32_bf16 v[108:111], v[144:147], v[208:211], v[108:111]
	v_mfma_f32_16x16x32_bf16 v[104:107], v[152:155], v[208:211], v[104:107]
	v_mfma_f32_16x16x32_bf16 v[92:95], v[144:147], v[236:239], v[92:95]
	v_mfma_f32_16x16x32_bf16 v[88:91], v[152:155], v[236:239], v[88:91]
	v_mfma_f32_16x16x32_bf16 v[76:79], v[144:147], v[244:247], v[76:79]
	v_mfma_f32_16x16x32_bf16 v[72:75], v[152:155], v[244:247], v[72:75]
	v_mfma_f32_16x16x32_bf16 v[124:127], v[148:151], v[204:207], v[124:127]
	v_mfma_f32_16x16x32_bf16 v[120:123], v[156:159], v[204:207], v[120:123]
	v_mfma_f32_16x16x32_bf16 v[108:111], v[148:151], v[232:235], v[108:111]
	v_mfma_f32_16x16x32_bf16 v[104:107], v[156:159], v[232:235], v[104:107]
	v_mfma_f32_16x16x32_bf16 v[92:95], v[148:151], v[240:243], v[92:95]
	v_mfma_f32_16x16x32_bf16 v[88:91], v[156:159], v[240:243], v[88:91]
	v_mfma_f32_16x16x32_bf16 v[76:79], v[148:151], v[248:251], v[76:79]
	v_mfma_f32_16x16x32_bf16 v[72:75], v[156:159], v[248:251], v[72:75]
	v_mfma_f32_16x16x32_bf16 v[116:119], v[184:187], v[200:203], v[116:119]
	v_mfma_f32_16x16x32_bf16 v[112:115], v[192:195], v[200:203], v[112:115]
	v_mfma_f32_16x16x32_bf16 v[100:103], v[184:187], v[208:211], v[100:103]
	v_mfma_f32_16x16x32_bf16 v[96:99], v[192:195], v[208:211], v[96:99]
	v_mfma_f32_16x16x32_bf16 v[84:87], v[184:187], v[236:239], v[84:87]
	v_mfma_f32_16x16x32_bf16 v[80:83], v[192:195], v[236:239], v[80:83]
	v_mfma_f32_16x16x32_bf16 v[68:71], v[184:187], v[244:247], v[68:71]
	v_mfma_f32_16x16x32_bf16 v[64:67], v[192:195], v[244:247], v[64:67]
	v_mfma_f32_16x16x32_bf16 v[116:119], v[188:191], v[204:207], v[116:119]
	v_mfma_f32_16x16x32_bf16 v[112:115], v[196:199], v[204:207], v[112:115]
	v_mfma_f32_16x16x32_bf16 v[100:103], v[188:191], v[232:235], v[100:103]
	v_mfma_f32_16x16x32_bf16 v[96:99], v[196:199], v[232:235], v[96:99]
	v_mfma_f32_16x16x32_bf16 v[84:87], v[188:191], v[240:243], v[84:87]
	v_mfma_f32_16x16x32_bf16 v[80:83], v[196:199], v[240:243], v[80:83]
	v_mfma_f32_16x16x32_bf16 v[68:71], v[188:191], v[248:251], v[68:71]
	v_mfma_f32_16x16x32_bf16 v[64:67], v[196:199], v[248:251], v[64:67]
	s_barrier
	s_add_i32 s24, s24, s57
	v_lshl_add_u64 v[160:161], s[0:1], 0, v[132:133]
	s_mov_b32 m0, s24
	ds_read_b128 v[200:203], v165 offset:16384
	ds_read_b128 v[204:207], v165 offset:17408
	ds_read_b128 v[208:211], v165 offset:18432
	ds_read_b128 v[232:235], v165 offset:19456
	ds_read_b128 v[236:239], v165 offset:20480
	ds_read_b128 v[240:243], v165 offset:21504
	ds_read_b128 v[244:247], v165 offset:22528
	ds_read_b128 v[248:251], v165 offset:23552
	global_load_lds_dwordx4 v[160:161], off
	s_add_i32 m0, s24, 0x2000
	s_add_u32 s24, s0, 0x80000
	v_lshl_add_u64 v[166:167], s[0:1], 0, v[128:129]
	s_addc_u32 s25, s1, 0
	s_add_i32 s55, s55, s57
	global_load_lds_dwordx4 v[166:167], off
	v_lshl_add_u64 v[170:171], s[24:25], 0, v[132:133]
	s_mov_b32 m0, s55
	v_lshl_add_u64 v[212:213], s[42:43], 0, v[130:131]
	global_load_lds_dwordx4 v[170:171], off
	v_lshl_add_u64 v[170:171], s[24:25], 0, v[128:129]
	s_add_i32 m0, s55, 0x2000
	s_nop 0
	global_load_lds_dwordx4 v[170:171], off
	v_lshl_add_u64 v[170:171], s[42:43], 0, v[134:135]
	s_mov_b32 m0, s58
	s_nop 0
	global_load_lds_dwordx4 v[170:171], off
	s_mov_b32 m0, s59
	s_nop 0
	global_load_lds_dwordx4 v[212:213], off
	s_waitcnt vmcnt(8)
	s_waitcnt lgkmcnt(0)
	s_barrier
; #define PG8_STAGE(bufoff, gbase, voff) do { _Pragma("unroll") for (int _i = 0; _i < 2; ++_i) \
;         __builtin_amdgcn_global_load_lds((const unsigned*)((const char*)(gbase) + (voff)[_i]), (LAS unsigned*)(lds + (bufoff) + ldsw + _i * 8192), 16, 0, 0); } while (0)
; #define PG8_LDA(dst, b, h) do { _Pragma("unroll") for (int m = 0; m < 4; ++m) _Pragma("unroll") for (int k = 0; k < 2; ++k) dst[m][k] = *(const LAS bf16x8*)(lds + PG8_SA(b, h) + aoff + m * 2048 + k * 1024); } while (0)
; #define PG8_LDB(dst, b, h) do { _Pragma("unroll") for (int n = 0; n < 2; ++n) _Pragma("unroll") for (int k = 0; k < 2; ++k) dst[n][k] = *(const LAS bf16x8*)(lds + PG8_SB(b, h) + boff + n * 2048 + k * 1024); } while (0)
; #define PG8_MMA(ai, bj, At, Bt) do { __builtin_amdgcn_s_setprio(1); _Pragma("unroll") for (int m = 0; m < 4; ++m) _Pragma("unroll") for (int n = 0; n < 2; ++n) _Pragma("unroll") for (int k = 0; k < 2; ++k) \
;         acc[ai][bj][m][n] = __builtin_amdgcn_mfma_f32_16x16x32_bf16(Bt[n][k], At[m][k], acc[ai][bj][m][n], 0, 0, 0); __builtin_amdgcn_s_setprio(0); } while (0)
; #define PG8_WAIT_V(n) asm volatile("s_waitcnt vmcnt(" #n ")" ::: "memory")
; #define PG8_WAIT_L(n) asm volatile("s_waitcnt lgkmcnt(" #n ")" ::: "memory")
; #define PG8_BAR __builtin_amdgcn_s_barrier()
; #define PG8_SCHED __builtin_amdgcn_sched_barrier(0)
; template <class Epi>
; __device__ __forceinline__ void gemm_phase(LAS unsigned char* lds, const Gemm g, const StaticOrder& S, const Epi& E, const int tid) {
;     ...
;             PG8_WAIT_V(8); PG8_WAIT_L(0); PG8_BAR; PG8_MMA(1, 0, At, B0); PG8_MMA(1, 1, At, B1); PG8_BAR; PG8_SCHED;
;             PG8_LDB(B0, 1, 0); PG8_LDB(B1, 1, 1); PG8_SCHED; PG8_LDA(At, 1, 0); PG8_STAGE(PG8_SA(0, 1), a2 + hsA, voffA);
;             PG8_WAIT_V(8); PG8_WAIT_L(0); PG8_BAR; PG8_MMA(0, 0, At, B0); PG8_MMA(0, 1, At, B1); PG8_BAR; PG8_SCHED;
	v_mfma_f32_16x16x32_bf16 v[60:63], v[144:147], v[200:203], v[60:63]
	v_mfma_f32_16x16x32_bf16 v[56:59], v[152:155], v[200:203], v[56:59]
	v_mfma_f32_16x16x32_bf16 v[44:47], v[144:147], v[208:211], v[44:47]
	v_mfma_f32_16x16x32_bf16 v[40:43], v[152:155], v[208:211], v[40:43]
	v_mfma_f32_16x16x32_bf16 v[28:31], v[144:147], v[236:239], v[28:31]
	v_mfma_f32_16x16x32_bf16 v[24:27], v[152:155], v[236:239], v[24:27]
	v_mfma_f32_16x16x32_bf16 v[12:15], v[144:147], v[244:247], v[12:15]
	v_mfma_f32_16x16x32_bf16 v[8:11], v[152:155], v[244:247], v[8:11]
	v_mfma_f32_16x16x32_bf16 v[60:63], v[148:151], v[204:207], v[60:63]
	v_mfma_f32_16x16x32_bf16 v[56:59], v[156:159], v[204:207], v[56:59]
	v_mfma_f32_16x16x32_bf16 v[44:47], v[148:151], v[232:235], v[44:47]
	v_mfma_f32_16x16x32_bf16 v[40:43], v[156:159], v[232:235], v[40:43]
	v_mfma_f32_16x16x32_bf16 v[28:31], v[148:151], v[240:243], v[28:31]
	v_mfma_f32_16x16x32_bf16 v[24:27], v[156:159], v[240:243], v[24:27]
	v_mfma_f32_16x16x32_bf16 v[12:15], v[148:151], v[248:251], v[12:15]
	v_mfma_f32_16x16x32_bf16 v[8:11], v[156:159], v[248:251], v[8:11]
	v_mfma_f32_16x16x32_bf16 v[52:55], v[184:187], v[200:203], v[52:55]
	v_mfma_f32_16x16x32_bf16 v[48:51], v[192:195], v[200:203], v[48:51]
	v_mfma_f32_16x16x32_bf16 v[36:39], v[184:187], v[208:211], v[36:39]
	v_mfma_f32_16x16x32_bf16 v[32:35], v[192:195], v[208:211], v[32:35]
	v_mfma_f32_16x16x32_bf16 v[20:23], v[184:187], v[236:239], v[20:23]
	v_mfma_f32_16x16x32_bf16 v[16:19], v[192:195], v[236:239], v[16:19]
	v_mfma_f32_16x16x32_bf16 v[4:7], v[184:187], v[244:247], v[4:7]
	v_mfma_f32_16x16x32_bf16 v[0:3], v[192:195], v[244:247], v[0:3]
	v_mfma_f32_16x16x32_bf16 v[52:55], v[188:191], v[204:207], v[52:55]
	v_mfma_f32_16x16x32_bf16 v[48:51], v[196:199], v[204:207], v[48:51]
	v_mfma_f32_16x16x32_bf16 v[36:39], v[188:191], v[232:235], v[36:39]
	v_mfma_f32_16x16x32_bf16 v[32:35], v[196:199], v[232:235], v[32:35]
	v_mfma_f32_16x16x32_bf16 v[20:23], v[188:191], v[240:243], v[20:23]
	v_mfma_f32_16x16x32_bf16 v[16:19], v[196:199], v[240:243], v[16:19]
	v_mfma_f32_16x16x32_bf16 v[4:7], v[188:191], v[248:251], v[4:7]
	v_mfma_f32_16x16x32_bf16 v[0:3], v[196:199], v[248:251], v[0:3]
	s_barrier
	s_add_i32 s55, 0, 0x18000
	v_add_u32_e32 v143, s55, v163
	s_add_i32 s67, 0, 0x1c000
	ds_read_b128 v[144:147], v143
	ds_read_b128 v[148:151], v143 offset:1024
	ds_read_b128 v[152:155], v143 offset:2048
	ds_read_b128 v[156:159], v143 offset:3072
	v_add_u32_e32 v143, s67, v163
	ds_read_b128 v[184:187], v143
	ds_read_b128 v[188:191], v143 offset:1024
	ds_read_b128 v[192:195], v143 offset:2048
	ds_read_b128 v[196:199], v143 offset:3072
	s_add_u32 s24, s42, 0x80000
	s_addc_u32 s25, s43, 0
	s_mov_b32 m0, s27
	v_lshl_add_u64 v[172:173], s[24:25], 0, v[134:135]
	ds_read_b128 v[200:203], v165 offset:32768
	ds_read_b128 v[204:207], v165 offset:33792
	ds_read_b128 v[208:211], v165 offset:34816
	ds_read_b128 v[232:235], v165 offset:35840
	ds_read_b128 v[236:239], v165 offset:36864
	ds_read_b128 v[240:243], v165 offset:37888
	ds_read_b128 v[244:247], v165 offset:38912
	ds_read_b128 v[248:251], v165 offset:39936
	global_load_lds_dwordx4 v[172:173], off
	v_lshl_add_u64 v[172:173], s[24:25], 0, v[130:131]
	s_mov_b32 m0, s96
	s_nop 0
	global_load_lds_dwordx4 v[172:173], off
	s_waitcnt vmcnt(8)
	s_waitcnt lgkmcnt(0)
	s_barrier
	v_mfma_f32_16x16x32_bf16 v[124:127], v[144:147], v[200:203], v[124:127]
	v_mfma_f32_16x16x32_bf16 v[120:123], v[152:155], v[200:203], v[120:123]
	v_mfma_f32_16x16x32_bf16 v[108:111], v[144:147], v[208:211], v[108:111]
	v_mfma_f32_16x16x32_bf16 v[104:107], v[152:155], v[208:211], v[104:107]
	v_mfma_f32_16x16x32_bf16 v[92:95], v[144:147], v[236:239], v[92:95]
	v_mfma_f32_16x16x32_bf16 v[88:91], v[152:155], v[236:239], v[88:91]
	v_mfma_f32_16x16x32_bf16 v[76:79], v[144:147], v[244:247], v[76:79]
	v_mfma_f32_16x16x32_bf16 v[72:75], v[152:155], v[244:247], v[72:75]
	v_mfma_f32_16x16x32_bf16 v[124:127], v[148:151], v[204:207], v[124:127]
	v_mfma_f32_16x16x32_bf16 v[120:123], v[156:159], v[204:207], v[120:123]
	v_mfma_f32_16x16x32_bf16 v[108:111], v[148:151], v[232:235], v[108:111]
	v_mfma_f32_16x16x32_bf16 v[104:107], v[156:159], v[232:235], v[104:107]
	v_mfma_f32_16x16x32_bf16 v[92:95], v[148:151], v[240:243], v[92:95]
	v_mfma_f32_16x16x32_bf16 v[88:91], v[156:159], v[240:243], v[88:91]
	v_mfma_f32_16x16x32_bf16 v[76:79], v[148:151], v[248:251], v[76:79]
	v_mfma_f32_16x16x32_bf16 v[72:75], v[156:159], v[248:251], v[72:75]
	v_mfma_f32_16x16x32_bf16 v[116:119], v[184:187], v[200:203], v[116:119]
	v_mfma_f32_16x16x32_bf16 v[112:115], v[192:195], v[200:203], v[112:115]
	v_mfma_f32_16x16x32_bf16 v[100:103], v[184:187], v[208:211], v[100:103]
	v_mfma_f32_16x16x32_bf16 v[96:99], v[192:195], v[208:211], v[96:99]
	v_mfma_f32_16x16x32_bf16 v[84:87], v[184:187], v[236:239], v[84:87]
	v_mfma_f32_16x16x32_bf16 v[80:83], v[192:195], v[236:239], v[80:83]
	v_mfma_f32_16x16x32_bf16 v[68:71], v[184:187], v[244:247], v[68:71]
	v_mfma_f32_16x16x32_bf16 v[64:67], v[192:195], v[244:247], v[64:67]
	v_mfma_f32_16x16x32_bf16 v[116:119], v[188:191], v[204:207], v[116:119]
	v_mfma_f32_16x16x32_bf16 v[112:115], v[196:199], v[204:207], v[112:115]
	v_mfma_f32_16x16x32_bf16 v[100:103], v[188:191], v[232:235], v[100:103]
	v_mfma_f32_16x16x32_bf16 v[96:99], v[196:199], v[232:235], v[96:99]
	v_mfma_f32_16x16x32_bf16 v[84:87], v[188:191], v[240:243], v[84:87]
	v_mfma_f32_16x16x32_bf16 v[80:83], v[196:199], v[240:243], v[80:83]
	v_mfma_f32_16x16x32_bf16 v[68:71], v[188:191], v[248:251], v[68:71]
	v_mfma_f32_16x16x32_bf16 v[64:67], v[196:199], v[248:251], v[64:67]
	s_barrier
; #define PG8_STAGE(bufoff, gbase, voff) do { _Pragma("unroll") for (int _i = 0; _i < 2; ++_i) \
;         __builtin_amdgcn_global_load_lds((const unsigned*)((const char*)(gbase) + (voff)[_i]), (LAS unsigned*)(lds + (bufoff) + ldsw + _i * 8192), 16, 0, 0); } while (0)
; #define PG8_LDA(dst, b, h) do { _Pragma("unroll") for (int m = 0; m < 4; ++m) _Pragma("unroll") for (int k = 0; k < 2; ++k) dst[m][k] = *(const LAS bf16x8*)(lds + PG8_SA(b, h) + aoff + m * 2048 + k * 1024); } while (0)
; #define PG8_MMA(ai, bj, At, Bt) do { __builtin_amdgcn_s_setprio(1); _Pragma("unroll") for (int m = 0; m < 4; ++m) _Pragma("unroll") for (int n = 0; n < 2; ++n) _Pragma("unroll") for (int k = 0; k < 2; ++k) \
;         acc[ai][bj][m][n] = __builtin_amdgcn_mfma_f32_16x16x32_bf16(Bt[n][k], At[m][k], acc[ai][bj][m][n], 0, 0, 0); __builtin_amdgcn_s_setprio(0); } while (0)
; #define PG8_WAIT_V(n) asm volatile("s_waitcnt vmcnt(" #n ")" ::: "memory")
; #define PG8_WAIT_L(n) asm volatile("s_waitcnt lgkmcnt(" #n ")" ::: "memory")
; #define PG8_BAR __builtin_amdgcn_s_barrier()
; #define PG8_SCHED __builtin_amdgcn_sched_barrier(0)
; template <class Epi>
; __device__ __forceinline__ void gemm_phase(LAS unsigned char* lds, const Gemm g, const StaticOrder& S, const Epi& E, const int tid) {
;     ...
;             PG8_LDA(At, 1, 1); PG8_STAGE(PG8_SB(1, 0), b3, voffB); PG8_STAGE(PG8_SB(1, 1), b3 + hsB, voffB); PG8_STAGE(PG8_SA(1, 0), a3, voffA);
;             PG8_WAIT_V(8); PG8_WAIT_L(0); PG8_BAR; PG8_MMA(1, 0, At, B0); PG8_MMA(1, 1, At, B1); PG8_BAR; PG8_SCHED;
;         }
;         if (wr == 0) PG8_BAR;
;     __device__ __forceinline__ void operator()(f32x4 (&acc)[2][2][4][2], const Unit& u, int wr, int wc, int fr, int fq) const {
;     ...
;         bf16* dst; int ld, c0; bool sg = false;
;         if (u.pn < 12) { dst = UA; ld = 3072; c0 = u.pn * 256; }
;         else if (u.pn < 28) { dst = UB; ld = 4096; c0 = (u.pn - 12) * 256; }
;         else if (u.pn < 42) { dst = UC; ld = 3584; c0 = (u.pn - 28) * 256; }
;         else { dst = UG; ld = 6144; c0 = (u.pn - 42) * 256; sg = true; }
	s_add_i32 s24, s55, s57
	v_lshl_add_u64 v[160:161], v[160:161], 0, s[28:29]
	s_mov_b32 m0, s24
	ds_read_b128 v[200:203], v165 offset:49152
	ds_read_b128 v[204:207], v165 offset:50176
	ds_read_b128 v[208:211], v165 offset:51200
	ds_read_b128 v[232:235], v165 offset:52224
	ds_read_b128 v[236:239], v165 offset:53248
	ds_read_b128 v[240:243], v165 offset:54272
	ds_read_b128 v[244:247], v165 offset:55296
	ds_read_b128 v[248:251], v165 offset:56320
	global_load_lds_dwordx4 v[160:161], off
	s_add_i32 m0, s24, 0x2000
	s_add_u32 s0, s0, 0x80080
	v_lshl_add_u64 v[160:161], v[166:167], 0, s[28:29]
	s_addc_u32 s1, s1, 0
	s_add_i32 s24, s67, s57
	global_load_lds_dwordx4 v[160:161], off
	v_lshl_add_u64 v[160:161], s[0:1], 0, v[132:133]
	s_mov_b32 m0, s24
	s_nop 0
	global_load_lds_dwordx4 v[160:161], off
	v_lshl_add_u64 v[160:161], s[0:1], 0, v[128:129]
	s_add_i32 m0, s24, 0x2000
	s_nop 0
	global_load_lds_dwordx4 v[160:161], off
	v_lshl_add_u64 v[160:161], v[170:171], 0, s[28:29]
	s_mov_b32 m0, s6
	s_nop 0
	global_load_lds_dwordx4 v[160:161], off
	v_lshl_add_u64 v[160:161], v[212:213], 0, s[28:29]
	s_mov_b32 m0, s7
	s_nop 0
	global_load_lds_dwordx4 v[160:161], off
	s_waitcnt vmcnt(8)
	s_waitcnt lgkmcnt(0)
	s_barrier
	v_mfma_f32_16x16x32_bf16 v[60:63], v[144:147], v[200:203], v[60:63]
	v_mfma_f32_16x16x32_bf16 v[56:59], v[152:155], v[200:203], v[56:59]
	v_mfma_f32_16x16x32_bf16 v[44:47], v[144:147], v[208:211], v[44:47]
	v_mfma_f32_16x16x32_bf16 v[40:43], v[152:155], v[208:211], v[40:43]
	v_mfma_f32_16x16x32_bf16 v[28:31], v[144:147], v[236:239], v[28:31]
	v_mfma_f32_16x16x32_bf16 v[24:27], v[152:155], v[236:239], v[24:27]
	v_mfma_f32_16x16x32_bf16 v[12:15], v[144:147], v[244:247], v[12:15]
	v_mfma_f32_16x16x32_bf16 v[8:11], v[152:155], v[244:247], v[8:11]
	v_mfma_f32_16x16x32_bf16 v[60:63], v[148:151], v[204:207], v[60:63]
	v_mfma_f32_16x16x32_bf16 v[56:59], v[156:159], v[204:207], v[56:59]
	v_mfma_f32_16x16x32_bf16 v[44:47], v[148:151], v[232:235], v[44:47]
	v_mfma_f32_16x16x32_bf16 v[40:43], v[156:159], v[232:235], v[40:43]
	v_mfma_f32_16x16x32_bf16 v[28:31], v[148:151], v[240:243], v[28:31]
	v_mfma_f32_16x16x32_bf16 v[24:27], v[156:159], v[240:243], v[24:27]
	v_mfma_f32_16x16x32_bf16 v[12:15], v[148:151], v[248:251], v[12:15]
	v_mfma_f32_16x16x32_bf16 v[8:11], v[156:159], v[248:251], v[8:11]
	v_mfma_f32_16x16x32_bf16 v[52:55], v[184:187], v[200:203], v[52:55]
	v_mfma_f32_16x16x32_bf16 v[48:51], v[192:195], v[200:203], v[48:51]
	v_mfma_f32_16x16x32_bf16 v[36:39], v[184:187], v[208:211], v[36:39]
	v_mfma_f32_16x16x32_bf16 v[32:35], v[192:195], v[208:211], v[32:35]
	v_mfma_f32_16x16x32_bf16 v[20:23], v[184:187], v[236:239], v[20:23]
	v_mfma_f32_16x16x32_bf16 v[16:19], v[192:195], v[236:239], v[16:19]
	v_mfma_f32_16x16x32_bf16 v[4:7], v[184:187], v[244:247], v[4:7]
	v_mfma_f32_16x16x32_bf16 v[0:3], v[192:195], v[244:247], v[0:3]
	v_mfma_f32_16x16x32_bf16 v[52:55], v[188:191], v[204:207], v[52:55]
	v_mfma_f32_16x16x32_bf16 v[48:51], v[196:199], v[204:207], v[48:51]
	v_mfma_f32_16x16x32_bf16 v[36:39], v[188:191], v[232:235], v[36:39]
	v_mfma_f32_16x16x32_bf16 v[32:35], v[196:199], v[232:235], v[32:35]
	v_mfma_f32_16x16x32_bf16 v[20:23], v[188:191], v[240:243], v[20:23]
	v_mfma_f32_16x16x32_bf16 v[16:19], v[196:199], v[240:243], v[16:19]
	v_mfma_f32_16x16x32_bf16 v[4:7], v[188:191], v[248:251], v[4:7]
	v_mfma_f32_16x16x32_bf16 v[0:3], v[196:199], v[248:251], v[0:3]
	s_barrier
	s_add_i32 vcc_hi, vcc_hi, 2
	s_add_u32 s36, s36, 0x100
	s_addc_u32 s37, s37, 0
	s_add_u32 s69, s69, 0x100
	s_addc_u32 vcc_lo, vcc_lo, 0
	s_cmp_gt_u32 vcc_hi, 29
	s_cbranch_scc0 .LBB0_354
.LBB0_357:
	s_setprio 0
	v_lshl_add_u32 v166, s60, 8, v162
	s_cmp_gt_i32 s45, 7
	s_mov_b64 s[0:1], -1
	s_cbranch_scc0 .LBB0_421
	s_cmp_gt_u32 s45, 11
	s_mov_b64 s[10:11], -1
	s_cbranch_scc0 .LBB0_368
	s_lshl_b32 s49, s45, 8
	s_cmp_gt_u32 s45, 27
	s_cbranch_scc0 .LBB0_365
	s_mov_b64 s[0:1], -1
	s_cmp_gt_u32 s45, 41
	s_cbranch_scc0 .LBB0_362
	s_add_i32 s47, s49, 0xffffd600
	s_mov_b64 s[10:11], 0

; __device__ __forceinline__ unsigned cvt_pk_bf16(float lo, float hi) { unsigned r; asm volatile("v_cvt_pk_bf16_f32 %0, %1, %2" : "=v"(r) : "v"(lo), "v"(hi)); return r; }
; #define PG8_BAR __builtin_amdgcn_s_barrier()
; template <class Epi>
; __device__ __forceinline__ void gemm_phase(LAS unsigned char* lds, const Gemm g, const StaticOrder& S, const Epi& E, const int tid) {
;     ...
;         if (wr == 0) PG8_BAR;
;         E(acc, cur, wr, wc, fr, fq);
;     __device__ __forceinline__ void operator()(f32x4 (&acc)[2][2][4][2], const Unit& u, int wr, int wc, int fr, int fq) const {
;         const int row0 = u.pm * BM + wr * 64 + fr, col0 = u.pn * 128 + wc * 32 + 8 * fq;
; #pragma unroll
;         for (int ai = 0; ai < 2; ++ai)
; #pragma unroll
;             for (int m = 0; m < 4; ++m) {
;                 bf16* rowp = O + (size_t)(row0 + ai * HALF + m * 16) * FF + col0;
;                 const f32x4 g0 = acc[ai][0][m][0], g1 = acc[ai][0][m][1], u0 = acc[ai][1][m][0], u1 = acc[ai][1][m][1];
;                 u32x4 w;
;                 const f32x4 a0 = swiglu4(g0, u0), a1 = swiglu4(g1, u1);
;                 w.x = cvt_pk_bf16(a0[0], a0[1]); w.y = cvt_pk_bf16(a0[2], a0[3]); w.z = cvt_pk_bf16(a1[0], a1[1]); w.w = cvt_pk_bf16(a1[2], a1[3]);
;                 __builtin_nontemporal_store(w, (u32x4*)rowp);
;             }
.LBB0_1007:
	s_setprio 0
	v_pk_mul_f32 v[150:151], v[126:127], s[74:75] op_sel_hi:[1,0]
	v_pk_mul_f32 v[152:153], v[124:125], s[74:75] op_sel_hi:[1,0]
	v_pk_mul_f32 v[122:123], v[126:127], v[122:123]
	v_pk_mul_f32 v[120:121], v[124:125], v[120:121]
	v_pk_mul_f32 v[124:125], v[118:119], s[74:75] op_sel_hi:[1,0]
	v_pk_mul_f32 v[126:127], v[116:117], s[74:75] op_sel_hi:[1,0]
	v_exp_f32_e32 v124, v124
	v_exp_f32_e32 v126, v126
	v_exp_f32_e32 v125, v125
	v_exp_f32_e32 v127, v127
	v_exp_f32_e32 v152, v152
	v_exp_f32_e32 v150, v150
	v_exp_f32_e32 v151, v151
	v_exp_f32_e32 v153, v153
	v_pk_add_f32 v[124:125], v[124:125], 1.0 op_sel_hi:[1,0]
	v_pk_add_f32 v[126:127], v[126:127], 1.0 op_sel_hi:[1,0]
	v_pk_add_f32 v[150:151], v[150:151], 1.0 op_sel_hi:[1,0]
	v_pk_add_f32 v[152:153], v[152:153], 1.0 op_sel_hi:[1,0]
	v_rcp_f32_e32 v126, v126
	v_rcp_f32_e32 v124, v124
	v_rcp_f32_e32 v125, v125
	v_rcp_f32_e32 v127, v127
	v_readlane_b32 s0, v254, 23
	v_rcp_f32_e32 v152, v152
	v_rcp_f32_e32 v153, v153
	v_rcp_f32_e32 v150, v150
	v_rcp_f32_e32 v151, v151
	v_lshl_or_b32 v140, s47, 7, v144
	v_readlane_b32 s1, v254, 24
	v_lshl_add_u32 v146, s48, 8, v142
	v_ashrrev_i32_e32 v141, 31, v140
	v_mov_b64_e32 v[138:139], s[0:1]
	s_movk_i32 s2, 0x2c00
	v_pk_mul_f32 v[114:115], v[118:119], v[114:115]
	v_pk_mul_f32 v[112:113], v[116:117], v[112:113]
	v_mad_i64_i32 v[148:149], s[0:1], v146, s2, v[138:139]
	v_lshlrev_b64 v[140:141], 1, v[140:141]
	v_pk_mul_f32 v[116:117], v[124:125], v[114:115]
	v_pk_mul_f32 v[114:115], v[126:127], v[112:113]
	v_lshl_add_u64 v[148:149], v[148:149], 0, v[140:141]
	v_pk_mul_f32 v[122:123], v[150:151], v[122:123]
	v_pk_mul_f32 v[120:121], v[152:153], v[120:121]
	v_pk_mul_f32 v[106:107], v[110:111], v[106:107]
	v_cvt_pk_bf16_f32 v112, v120, v121
	v_cvt_pk_bf16_f32 v113, v122, v123
	v_cvt_pk_bf16_f32 v114, v114, v115
	v_cvt_pk_bf16_f32 v115, v116, v117
	global_store_dwordx4 v[148:149], v[112:115], off nt
	v_pk_mul_f32 v[104:105], v[108:109], v[104:105]
	v_or_b32_e32 v116, 16, v146
	v_pk_mul_f32 v[112:113], v[110:111], s[74:75] op_sel_hi:[1,0]
	v_pk_mul_f32 v[114:115], v[108:109], s[74:75] op_sel_hi:[1,0]
	v_pk_mul_f32 v[108:109], v[102:103], s[74:75] op_sel_hi:[1,0]
	v_pk_mul_f32 v[110:111], v[100:101], s[74:75] op_sel_hi:[1,0]
	v_exp_f32_e32 v108, v108
	v_exp_f32_e32 v110, v110
	v_exp_f32_e32 v109, v109
	v_exp_f32_e32 v111, v111
	v_exp_f32_e32 v114, v114
	v_exp_f32_e32 v115, v115
	v_exp_f32_e32 v112, v112
	v_exp_f32_e32 v113, v113
	v_pk_add_f32 v[108:109], v[108:109], 1.0 op_sel_hi:[1,0]
	v_pk_add_f32 v[110:111], v[110:111], 1.0 op_sel_hi:[1,0]
	v_pk_add_f32 v[114:115], v[114:115], 1.0 op_sel_hi:[1,0]
	v_pk_add_f32 v[112:113], v[112:113], 1.0 op_sel_hi:[1,0]
	v_rcp_f32_e32 v110, v110
	v_rcp_f32_e32 v108, v108
	v_rcp_f32_e32 v109, v109
	v_rcp_f32_e32 v111, v111
	v_rcp_f32_e32 v114, v114
	v_rcp_f32_e32 v115, v115
	v_rcp_f32_e32 v112, v112
	v_rcp_f32_e32 v113, v113
	v_pk_mul_f32 v[98:99], v[102:103], v[98:99]
	v_pk_mul_f32 v[96:97], v[100:101], v[96:97]
	v_mad_i64_i32 v[116:117], s[0:1], v116, s2, v[138:139]
	v_pk_mul_f32 v[100:101], v[108:109], v[98:99]
	v_pk_mul_f32 v[98:99], v[110:111], v[96:97]
	v_lshl_add_u64 v[116:117], v[116:117], 0, v[140:141]
	v_pk_mul_f32 v[106:107], v[112:113], v[106:107]
	v_pk_mul_f32 v[104:105], v[114:115], v[104:105]
	v_pk_mul_f32 v[90:91], v[94:95], v[90:91]
	v_cvt_pk_bf16_f32 v96, v104, v105
	v_cvt_pk_bf16_f32 v97, v106, v107
	v_cvt_pk_bf16_f32 v98, v98, v99
	v_cvt_pk_bf16_f32 v99, v100, v101
	global_store_dwordx4 v[116:117], v[96:99], off nt
	v_pk_mul_f32 v[88:89], v[92:93], v[88:89]
	v_or_b32_e32 v100, 32, v146
	v_pk_mul_f32 v[96:97], v[94:95], s[74:75] op_sel_hi:[1,0]
	v_pk_mul_f32 v[98:99], v[92:93], s[74:75] op_sel_hi:[1,0]
	v_pk_mul_f32 v[92:93], v[86:87], s[74:75] op_sel_hi:[1,0]
	v_pk_mul_f32 v[94:95], v[84:85], s[74:75] op_sel_hi:[1,0]
	v_exp_f32_e32 v92, v92
	v_exp_f32_e32 v94, v94
	v_exp_f32_e32 v93, v93
	v_exp_f32_e32 v95, v95
	v_exp_f32_e32 v98, v98
	v_exp_f32_e32 v99, v99
	v_exp_f32_e32 v96, v96
	v_exp_f32_e32 v97, v97
	v_pk_add_f32 v[92:93], v[92:93], 1.0 op_sel_hi:[1,0]
	v_pk_add_f32 v[94:95], v[94:95], 1.0 op_sel_hi:[1,0]
	v_pk_add_f32 v[98:99], v[98:99], 1.0 op_sel_hi:[1,0]
	v_pk_add_f32 v[96:97], v[96:97], 1.0 op_sel_hi:[1,0]
	v_rcp_f32_e32 v94, v94
	v_rcp_f32_e32 v92, v92
	v_rcp_f32_e32 v93, v93
	v_rcp_f32_e32 v95, v95
	v_rcp_f32_e32 v98, v98
	v_rcp_f32_e32 v99, v99
	v_rcp_f32_e32 v96, v96
	v_rcp_f32_e32 v97, v97
	v_pk_mul_f32 v[82:83], v[86:87], v[82:83]
	v_pk_mul_f32 v[80:81], v[84:85], v[80:81]
	v_mad_i64_i32 v[100:101], s[0:1], v100, s2, v[138:139]
	v_pk_mul_f32 v[84:85], v[92:93], v[82:83]
	v_pk_mul_f32 v[82:83], v[94:95], v[80:81]
	v_lshl_add_u64 v[100:101], v[100:101], 0, v[140:141]
	v_pk_mul_f32 v[90:91], v[96:97], v[90:91]
	v_pk_mul_f32 v[88:89], v[98:99], v[88:89]
	v_pk_mul_f32 v[74:75], v[78:79], v[74:75]
	v_cvt_pk_bf16_f32 v80, v88, v89
	v_cvt_pk_bf16_f32 v81, v90, v91
	v_cvt_pk_bf16_f32 v82, v82, v83
	v_cvt_pk_bf16_f32 v83, v84, v85
	global_store_dwordx4 v[100:101], v[80:83], off nt
	v_pk_mul_f32 v[72:73], v[76:77], v[72:73]
	v_or_b32_e32 v84, 48, v146
	v_pk_mul_f32 v[80:81], v[78:79], s[74:75] op_sel_hi:[1,0]
	v_pk_mul_f32 v[82:83], v[76:77], s[74:75] op_sel_hi:[1,0]
	v_pk_mul_f32 v[76:77], v[70:71], s[74:75] op_sel_hi:[1,0]
	v_pk_mul_f32 v[78:79], v[68:69], s[74:75] op_sel_hi:[1,0]
	v_exp_f32_e32 v76, v76
	v_exp_f32_e32 v78, v78
	v_exp_f32_e32 v77, v77
	v_exp_f32_e32 v79, v79
	v_exp_f32_e32 v82, v82
	v_exp_f32_e32 v83, v83
	v_exp_f32_e32 v80, v80
	v_exp_f32_e32 v81, v81
	v_pk_add_f32 v[76:77], v[76:77], 1.0 op_sel_hi:[1,0]
	v_pk_add_f32 v[78:79], v[78:79], 1.0 op_sel_hi:[1,0]
; __device__ __forceinline__ unsigned cvt_pk_bf16(float lo, float hi) { unsigned r; asm volatile("v_cvt_pk_bf16_f32 %0, %1, %2" : "=v"(r) : "v"(lo), "v"(hi)); return r; }
; #define PG8_BAR __builtin_amdgcn_s_barrier()
; template <class Epi>
; __device__ __forceinline__ void gemm_phase(LAS unsigned char* lds, const Gemm g, const StaticOrder& S, const Epi& E, const int tid) {
;     ...
;         if (wr == 0) PG8_BAR;
;         E(acc, cur, wr, wc, fr, fq);
;     __device__ __forceinline__ void operator()(f32x4 (&acc)[2][2][4][2], const Unit& u, int wr, int wc, int fr, int fq) const {
;     ...
;             for (int m = 0; m < 4; ++m) {
;                 bf16* rowp = O + (size_t)(row0 + ai * HALF + m * 16) * FF + col0;
;                 const f32x4 g0 = acc[ai][0][m][0], g1 = acc[ai][0][m][1], u0 = acc[ai][1][m][0], u1 = acc[ai][1][m][1];
;                 u32x4 w;
;                 const f32x4 a0 = swiglu4(g0, u0), a1 = swiglu4(g1, u1);
;                 w.x = cvt_pk_bf16(a0[0], a0[1]); w.y = cvt_pk_bf16(a0[2], a0[3]); w.z = cvt_pk_bf16(a1[0], a1[1]); w.w = cvt_pk_bf16(a1[2], a1[3]);
;                 __builtin_nontemporal_store(w, (u32x4*)rowp);
;             }
	v_pk_add_f32 v[82:83], v[82:83], 1.0 op_sel_hi:[1,0]
	v_pk_add_f32 v[80:81], v[80:81], 1.0 op_sel_hi:[1,0]
	v_rcp_f32_e32 v78, v78
	v_rcp_f32_e32 v76, v76
	v_rcp_f32_e32 v77, v77
	v_rcp_f32_e32 v79, v79
	v_rcp_f32_e32 v82, v82
	v_rcp_f32_e32 v83, v83
	v_rcp_f32_e32 v80, v80
	v_rcp_f32_e32 v81, v81
	v_pk_mul_f32 v[66:67], v[70:71], v[66:67]
	v_pk_mul_f32 v[64:65], v[68:69], v[64:65]
	v_mad_i64_i32 v[84:85], s[0:1], v84, s2, v[138:139]
	v_pk_mul_f32 v[68:69], v[76:77], v[66:67]
	v_pk_mul_f32 v[66:67], v[78:79], v[64:65]
	v_lshl_add_u64 v[84:85], v[84:85], 0, v[140:141]
	v_pk_mul_f32 v[74:75], v[80:81], v[74:75]
	v_pk_mul_f32 v[72:73], v[82:83], v[72:73]
	v_pk_mul_f32 v[58:59], v[62:63], v[58:59]
	v_cvt_pk_bf16_f32 v64, v72, v73
	v_cvt_pk_bf16_f32 v65, v74, v75
	v_cvt_pk_bf16_f32 v66, v66, v67
	v_cvt_pk_bf16_f32 v67, v68, v69
	global_store_dwordx4 v[84:85], v[64:67], off nt
	v_pk_mul_f32 v[56:57], v[60:61], v[56:57]
	v_add_u32_e32 v68, 0x80, v146
	v_pk_mul_f32 v[64:65], v[62:63], s[74:75] op_sel_hi:[1,0]
	v_pk_mul_f32 v[66:67], v[60:61], s[74:75] op_sel_hi:[1,0]
	v_pk_mul_f32 v[60:61], v[54:55], s[74:75] op_sel_hi:[1,0]
	v_pk_mul_f32 v[62:63], v[52:53], s[74:75] op_sel_hi:[1,0]
	v_exp_f32_e32 v60, v60
	v_exp_f32_e32 v62, v62
	v_exp_f32_e32 v61, v61
	v_exp_f32_e32 v63, v63
	v_exp_f32_e32 v66, v66
	v_exp_f32_e32 v67, v67
	v_exp_f32_e32 v64, v64
	v_exp_f32_e32 v65, v65
	v_pk_add_f32 v[60:61], v[60:61], 1.0 op_sel_hi:[1,0]
	v_pk_add_f32 v[62:63], v[62:63], 1.0 op_sel_hi:[1,0]
	v_pk_add_f32 v[66:67], v[66:67], 1.0 op_sel_hi:[1,0]
	v_pk_add_f32 v[64:65], v[64:65], 1.0 op_sel_hi:[1,0]
	v_rcp_f32_e32 v62, v62
	v_rcp_f32_e32 v60, v60
	v_rcp_f32_e32 v61, v61
	v_rcp_f32_e32 v63, v63
	v_rcp_f32_e32 v66, v66
	v_rcp_f32_e32 v67, v67
	v_rcp_f32_e32 v64, v64
	v_rcp_f32_e32 v65, v65
	v_pk_mul_f32 v[50:51], v[54:55], v[50:51]
	v_pk_mul_f32 v[48:49], v[52:53], v[48:49]
	v_mad_i64_i32 v[68:69], s[0:1], v68, s2, v[138:139]
	v_pk_mul_f32 v[52:53], v[60:61], v[50:51]
	v_pk_mul_f32 v[50:51], v[62:63], v[48:49]
	v_lshl_add_u64 v[68:69], v[68:69], 0, v[140:141]
	v_pk_mul_f32 v[58:59], v[64:65], v[58:59]
	v_pk_mul_f32 v[56:57], v[66:67], v[56:57]
	v_pk_mul_f32 v[42:43], v[46:47], v[42:43]
	v_cvt_pk_bf16_f32 v48, v56, v57
	v_cvt_pk_bf16_f32 v49, v58, v59
	v_cvt_pk_bf16_f32 v50, v50, v51
	v_cvt_pk_bf16_f32 v51, v52, v53
	global_store_dwordx4 v[68:69], v[48:51], off nt
	v_pk_mul_f32 v[40:41], v[44:45], v[40:41]
	v_add_u32_e32 v52, 0x90, v146
	v_pk_mul_f32 v[48:49], v[46:47], s[74:75] op_sel_hi:[1,0]
	v_pk_mul_f32 v[50:51], v[44:45], s[74:75] op_sel_hi:[1,0]
	v_pk_mul_f32 v[44:45], v[38:39], s[74:75] op_sel_hi:[1,0]
	v_pk_mul_f32 v[46:47], v[36:37], s[74:75] op_sel_hi:[1,0]
	v_exp_f32_e32 v44, v44
	v_exp_f32_e32 v46, v46
	v_exp_f32_e32 v45, v45
	v_exp_f32_e32 v47, v47
	v_exp_f32_e32 v50, v50
	v_exp_f32_e32 v51, v51
	v_exp_f32_e32 v48, v48
	v_exp_f32_e32 v49, v49
	v_pk_add_f32 v[44:45], v[44:45], 1.0 op_sel_hi:[1,0]
	v_pk_add_f32 v[46:47], v[46:47], 1.0 op_sel_hi:[1,0]
	v_pk_add_f32 v[50:51], v[50:51], 1.0 op_sel_hi:[1,0]
	v_pk_add_f32 v[48:49], v[48:49], 1.0 op_sel_hi:[1,0]
	v_rcp_f32_e32 v46, v46
	v_rcp_f32_e32 v44, v44
	v_rcp_f32_e32 v45, v45
	v_rcp_f32_e32 v47, v47
	v_rcp_f32_e32 v50, v50
	v_rcp_f32_e32 v51, v51
	v_rcp_f32_e32 v48, v48
	v_rcp_f32_e32 v49, v49
	v_pk_mul_f32 v[34:35], v[38:39], v[34:35]
	v_pk_mul_f32 v[32:33], v[36:37], v[32:33]
	v_mad_i64_i32 v[52:53], s[0:1], v52, s2, v[138:139]
	v_pk_mul_f32 v[36:37], v[44:45], v[34:35]
	v_pk_mul_f32 v[34:35], v[46:47], v[32:33]
	v_lshl_add_u64 v[52:53], v[52:53], 0, v[140:141]
	v_pk_mul_f32 v[42:43], v[48:49], v[42:43]
	v_pk_mul_f32 v[40:41], v[50:51], v[40:41]
	v_pk_mul_f32 v[26:27], v[30:31], v[26:27]
	v_cvt_pk_bf16_f32 v32, v40, v41
	v_cvt_pk_bf16_f32 v33, v42, v43
	v_cvt_pk_bf16_f32 v34, v34, v35
	v_cvt_pk_bf16_f32 v35, v36, v37
	global_store_dwordx4 v[52:53], v[32:35], off nt
	v_pk_mul_f32 v[24:25], v[28:29], v[24:25]
	v_add_u32_e32 v36, 0xa0, v146
	v_pk_mul_f32 v[32:33], v[30:31], s[74:75] op_sel_hi:[1,0]
	v_pk_mul_f32 v[34:35], v[28:29], s[74:75] op_sel_hi:[1,0]
	v_pk_mul_f32 v[28:29], v[22:23], s[74:75] op_sel_hi:[1,0]
	v_pk_mul_f32 v[30:31], v[20:21], s[74:75] op_sel_hi:[1,0]
	v_exp_f32_e32 v28, v28
	v_exp_f32_e32 v30, v30
	v_exp_f32_e32 v29, v29
	v_exp_f32_e32 v31, v31
	v_exp_f32_e32 v34, v34
	v_exp_f32_e32 v35, v35
	v_exp_f32_e32 v32, v32
	v_exp_f32_e32 v33, v33
	v_pk_add_f32 v[28:29], v[28:29], 1.0 op_sel_hi:[1,0]
	v_pk_add_f32 v[30:31], v[30:31], 1.0 op_sel_hi:[1,0]
	v_pk_add_f32 v[34:35], v[34:35], 1.0 op_sel_hi:[1,0]
	v_pk_add_f32 v[32:33], v[32:33], 1.0 op_sel_hi:[1,0]
	v_rcp_f32_e32 v30, v30
	v_rcp_f32_e32 v28, v28
	v_rcp_f32_e32 v29, v29
	v_rcp_f32_e32 v31, v31
	v_rcp_f32_e32 v34, v34
	v_rcp_f32_e32 v35, v35
	v_rcp_f32_e32 v32, v32
	v_rcp_f32_e32 v33, v33
	v_pk_mul_f32 v[18:19], v[22:23], v[18:19]
	v_pk_mul_f32 v[16:17], v[20:21], v[16:17]
	v_mad_i64_i32 v[36:37], s[0:1], v36, s2, v[138:139]
	v_pk_mul_f32 v[20:21], v[28:29], v[18:19]
	v_pk_mul_f32 v[18:19], v[30:31], v[16:17]
	v_lshl_add_u64 v[36:37], v[36:37], 0, v[140:141]
	v_pk_mul_f32 v[26:27], v[32:33], v[26:27]
	v_pk_mul_f32 v[24:25], v[34:35], v[24:25]
	v_pk_mul_f32 v[10:11], v[14:15], v[10:11]
	v_cvt_pk_bf16_f32 v16, v24, v25
	v_cvt_pk_bf16_f32 v17, v26, v27
	v_cvt_pk_bf16_f32 v18, v18, v19
	v_cvt_pk_bf16_f32 v19, v20, v21
	global_store_dwordx4 v[36:37], v[16:19], off nt
	v_pk_mul_f32 v[8:9], v[12:13], v[8:9]
	v_add_u32_e32 v20, 0xb0, v146
	v_pk_mul_f32 v[16:17], v[14:15], s[74:75] op_sel_hi:[1,0]
	v_pk_mul_f32 v[18:19], v[12:13], s[74:75] op_sel_hi:[1,0]
	v_pk_mul_f32 v[12:13], v[6:7], s[74:75] op_sel_hi:[1,0]
	v_pk_mul_f32 v[14:15], v[4:5], s[74:75] op_sel_hi:[1,0]
	v_exp_f32_e32 v12, v12
	v_exp_f32_e32 v14, v14
	v_exp_f32_e32 v13, v13
	v_exp_f32_e32 v15, v15
	v_exp_f32_e32 v18, v18
	v_exp_f32_e32 v19, v19
	v_exp_f32_e32 v16, v16
	v_exp_f32_e32 v17, v17
	v_pk_add_f32 v[12:13], v[12:13], 1.0 op_sel_hi:[1,0]
	v_pk_add_f32 v[14:15], v[14:15], 1.0 op_sel_hi:[1,0]
	v_pk_add_f32 v[18:19], v[18:19], 1.0 op_sel_hi:[1,0]
	v_pk_add_f32 v[16:17], v[16:17], 1.0 op_sel_hi:[1,0]
	v_rcp_f32_e32 v14, v14
	v_rcp_f32_e32 v12, v12
	v_rcp_f32_e32 v13, v13
	v_rcp_f32_e32 v15, v15
	v_rcp_f32_e32 v18, v18
	v_rcp_f32_e32 v19, v19
	v_rcp_f32_e32 v16, v16
	v_rcp_f32_e32 v17, v17
	v_mad_i64_i32 v[20:21], s[0:1], v20, s2, v[138:139]
	v_pk_mul_f32 v[2:3], v[6:7], v[2:3]
	v_pk_mul_f32 v[0:1], v[4:5], v[0:1]
	v_lshl_add_u64 v[20:21], v[20:21], 0, v[140:141]
	v_pk_mul_f32 v[4:5], v[12:13], v[2:3]
	v_pk_mul_f32 v[2:3], v[14:15], v[0:1]
	s_andn2_b64 vcc, exec, s[38:39]
	s_mov_b64 s[0:1], -1
	s_movk_i32 s49, 0x300
	s_mov_b64 s[52:53], 0x60000
	v_pk_mul_f32 v[10:11], v[16:17], v[10:11]
	v_pk_mul_f32 v[8:9], v[18:19], v[8:9]
	s_nop 0
	v_cvt_pk_bf16_f32 v0, v8, v9
	v_cvt_pk_bf16_f32 v1, v10, v11
	v_cvt_pk_bf16_f32 v2, v2, v3
	v_cvt_pk_bf16_f32 v3, v4, v5
	global_store_dwordx4 v[20:21], v[0:3], off nt
	s_cmp_eq_u64 s[8:9], 0
	s_cbranch_scc1 .Lepi_gu2_nb
	s_barrier
